# P2 conv: depthwise weights staged once per workgroup in LDS (ds_read_b128 instead of 24 global loads per 8 taps), waits re-derived
# speedup vs baseline: 1.0406x; 1.0017x over previous
.LBB0_272:
	s_cmp_lt_i32 s74, 3
	s_cselect_b64 s[2:3], -1, 0
	s_add_u32 s44, s72, 0x5a00000
	s_addc_u32 s45, s73, 0
	s_and_b64 s[2:3], s[2:3], s[0:1]
	s_andn2_b64 vcc, exec, s[2:3]
	s_cbranch_vccnz .LBB0_293
	v_lshlrev_b32_e32 v100, 4, v198
	v_readlane_b32 s4, v254, 40
	v_mov_b32_e32 v101, v100
	global_load_dwordx4 v[104:107], v101, s[62:63]
	v_add_u32_e32 v101, 0x2000, v100
	global_load_dwordx4 v[108:111], v101, s[62:63]
	v_add_u32_e32 v101, 0x4000, v100
	global_load_dwordx4 v[112:115], v101, s[62:63]
	v_add_u32_e32 v101, 0x6000, v100
	global_load_dwordx4 v[116:119], v101, s[62:63]
	v_add_u32_e32 v101, 0x8000, v100
	global_load_dwordx4 v[120:123], v101, s[62:63]
	v_add_u32_e32 v101, 0xa000, v100
	global_load_dwordx4 v[124:127], v101, s[62:63]
	v_add_u32_e32 v101, 0xc000, v100
	global_load_dwordx4 v[128:131], v101, s[62:63]
	v_add_u32_e32 v101, 0xe000, v100
	global_load_dwordx4 v[132:135], v101, s[62:63]
	v_add_u32_e32 v101, 0x10000, v100
	global_load_dwordx4 v[136:139], v101, s[62:63]
	v_add_u32_e32 v101, 0x12000, v100
	global_load_dwordx4 v[140:143], v101, s[62:63]
	v_add_u32_e32 v101, 0x14000, v100
	global_load_dwordx4 v[144:147], v101, s[62:63]
	s_cmp_lt_u32 s4, 5
	s_cbranch_scc0 .Lconv_pre_skip
	v_add_u32_e32 v101, 0x16000, v100
	global_load_dwordx4 v[148:151], v101, s[62:63]
.Lconv_pre_skip:
	s_waitcnt vmcnt(0)
	v_mov_b32_e32 v101, v100
	ds_write_b128 v101, v[104:107]
	v_add_u32_e32 v101, 0x2000, v100
	ds_write_b128 v101, v[108:111]
	v_add_u32_e32 v101, 0x4000, v100
	ds_write_b128 v101, v[112:115]
	v_add_u32_e32 v101, 0x6000, v100
	ds_write_b128 v101, v[116:119]
	v_add_u32_e32 v101, 0x8000, v100
	ds_write_b128 v101, v[120:123]
	v_add_u32_e32 v101, 0xa000, v100
	ds_write_b128 v101, v[124:127]
	v_add_u32_e32 v101, 0xc000, v100
	ds_write_b128 v101, v[128:131]
	v_add_u32_e32 v101, 0xe000, v100
	ds_write_b128 v101, v[132:135]
	v_add_u32_e32 v101, 0x10000, v100
	ds_write_b128 v101, v[136:139]
	v_add_u32_e32 v101, 0x12000, v100
	ds_write_b128 v101, v[140:143]
	v_add_u32_e32 v101, 0x14000, v100
	ds_write_b128 v101, v[144:147]
	s_cmp_lt_u32 s4, 5
	s_cbranch_scc0 .Lconv_pre_skip2
	v_add_u32_e32 v101, 0x16000, v100
	ds_write_b128 v101, v[148:151]
.Lconv_pre_skip2:
	s_waitcnt lgkmcnt(0)
	s_barrier
	v_readlane_b32 s0, v254, 41
	s_cmpk_gt_i32 s0, 0xfff
	s_cbranch_scc1 .LBB0_280
	v_lshlrev_b32_e32 v190, 4, v199
	v_mov_b32_e32 v86, 0
	v_readlane_b32 s4, v254, 23
	v_lshlrev_b32_e32 v2, 4, v199
	v_mov_b32_e32 v3, v86
	v_readlane_b32 s5, v254, 24
	v_mbcnt_lo_u32_b32 v1, -1, 0
	v_lshl_add_u64 v[88:89], s[64:65], 0, v[2:3]
	v_lshl_add_u64 v[92:93], s[62:63], 0, v[2:3]
	v_lshl_add_u64 v[94:95], s[66:67], 0, v[2:3]
	v_lshl_add_u64 v[96:97], s[4:5], 0, v[2:3]
	v_mbcnt_hi_u32_b32 v2, -1, v1
	v_and_b32_e32 v1, 64, v2
	v_add_u32_e32 v3, 64, v1
	v_xor_b32_e32 v1, 1, v2
	v_cmp_lt_i32_e32 vcc, v1, v3
	v_xor_b32_e32 v6, 2, v2
	v_readlane_b32 s1, v254, 40
	v_cndmask_b32_e32 v1, v2, v1, vcc
	v_cmp_lt_i32_e32 vcc, v6, v3
	s_lshl_b32 s0, s80, 5
	s_lshl_b32 s1, s1, 2
	v_cndmask_b32_e32 v6, v2, v6, vcc
	v_lshlrev_b32_e32 v162, 2, v6
	v_xor_b32_e32 v6, 4, v2
	v_cmp_lt_i32_e32 vcc, v6, v3
	v_lshlrev_b32_e32 v4, 3, v199
	v_mov_b32_e32 v5, v86
	v_cndmask_b32_e32 v6, v2, v6, vcc
	v_lshlrev_b32_e32 v163, 2, v6
	v_xor_b32_e32 v6, 8, v2
	v_cmp_lt_i32_e32 vcc, v6, v3
	v_readlane_b32 s8, v254, 27
	v_readlane_b32 s9, v254, 28
	v_cndmask_b32_e32 v6, v2, v6, vcc
	v_lshlrev_b32_e32 v164, 2, v6
	v_xor_b32_e32 v6, 16, v2
	v_cmp_lt_i32_e32 vcc, v6, v3
	v_readlane_b32 s10, v254, 29
	v_readlane_b32 s11, v254, 30
	v_cndmask_b32_e32 v6, v2, v6, vcc
	v_lshlrev_b32_e32 v165, 2, v6
	v_xor_b32_e32 v6, 32, v2
	v_cmp_lt_i32_e32 vcc, v6, v3
	v_readlane_b32 s12, v254, 31
	v_readlane_b32 s13, v254, 32
	v_readlane_b32 s14, v254, 33
	v_readlane_b32 s15, v254, 34
	v_cndmask_b32_e32 v2, v2, v6, vcc
	s_add_i32 s0, s0, s1
	v_lshl_add_u64 v[90:91], s[38:39], 0, v[4:5]
	v_lshlrev_b32_e32 v1, 2, v1
	v_lshlrev_b32_e32 v166, 2, v2
	v_lshl_add_u64 v[98:99], s[44:45], 0, v[4:5]
	s_sub_i32 s8, s0, 27
	s_lshl_b32 s9, s33, 5
	v_mov_b32_e32 v167, 0x600
	s_movk_i32 s10, 0x1000
	s_movk_i32 s11, 0x2000
	s_movk_i32 s12, 0x3000
	s_movk_i32 s13, 0x4000
	s_movk_i32 s14, 0x5000
	v_mov_b32_e32 v168, 0x3727c5ac
	v_readlane_b32 s15, v254, 41
	v_readlane_b32 s6, v254, 25
	v_readlane_b32 s7, v254, 26
	v_readlane_b32 s16, v254, 35
	v_readlane_b32 s17, v254, 36
	v_readlane_b32 s18, v254, 37
	v_readlane_b32 s19, v254, 38
	s_branch .LBB0_276

.LBB0_278:
	s_max_i32 s6, s5, 0
	v_mad_u64_u32 v[50:51], s[6:7], s6, v167, v[90:91]
	s_cmp_lt_i32 s5, 0
	v_lshl_add_u64 v[136:137], v[92:93], 0, s[0:1]
	v_add_u32_e32 v191, s0, v190
	s_cselect_b64 s[6:7], -1, 0
	s_add_i32 s18, s5, 1
	ds_read_b128 v[82:85], v191 offset:0
	ds_read_b128 v[78:81], v191 offset:1024
	ds_read_b128 v[74:77], v191 offset:2048
	global_load_dwordx2 v[148:149], v[50:51], off
	global_load_dwordx2 v[170:171], v[50:51], off offset:512
	global_load_dwordx2 v[172:173], v[50:51], off offset:1024
	s_max_i32 s16, s18, 0
	v_mad_u64_u32 v[50:51], s[16:17], s16, v167, v[90:91]
	global_load_dwordx2 v[174:175], v[50:51], off
	global_load_dwordx2 v[176:177], v[50:51], off offset:512
	global_load_dwordx2 v[178:179], v[50:51], off offset:1024
	s_nop 0
	ds_read_b128 v[50:53], v191 offset:3072
	v_add_co_u32_e32 v62, vcc, s10, v136
	s_cmp_lt_i32 s18, 0
	s_nop 0
	v_addc_co_u32_e32 v63, vcc, 0, v137, vcc
	v_add_co_u32_e32 v138, vcc, s11, v136
	s_cselect_b64 s[16:17], -1, 0
	s_nop 0
	v_addc_co_u32_e32 v139, vcc, 0, v137, vcc
	ds_read_b128 v[58:61], v191 offset:4096
	ds_read_b128 v[54:57], v191 offset:5120
	ds_read_b128 v[70:73], v191 offset:6144
	ds_read_b128 v[66:69], v191 offset:7168
	s_nop 0
	ds_read_b128 v[62:65], v191 offset:8192
	s_add_i32 s20, s5, 2
	s_max_i32 s18, s20, 0
	v_mad_u64_u32 v[140:141], s[18:19], s18, v167, v[90:91]
	global_load_dwordx2 v[144:145], v[140:141], off
	global_load_dwordx2 v[142:143], v[140:141], off offset:512
	s_nop 0
	global_load_dwordx2 v[140:141], v[140:141], off offset:1024
	s_cmp_lt_i32 s20, 0
	s_waitcnt vmcnt(9) lgkmcnt(8)
	v_pk_fma_f32 v[2:3], v[82:83], v[110:111], v[2:3]
	s_waitcnt vmcnt(9) lgkmcnt(7)
	v_pk_fma_f32 v[110:111], v[80:81], v[124:125], v[8:9]
	v_pk_fma_f32 v[150:151], v[78:79], v[116:117], v[6:7]
	s_waitcnt vmcnt(9) lgkmcnt(6)
	v_pk_fma_f32 v[152:153], v[74:75], v[128:129], v[10:11]
	s_waitcnt vmcnt(8) lgkmcnt(6)
	v_cndmask_b32_e64 v7, v148, 0, s[6:7]
	s_waitcnt vmcnt(7) lgkmcnt(6)
	v_cndmask_b32_e64 v9, v170, 0, s[6:7]
	s_waitcnt vmcnt(6) lgkmcnt(6)
	v_cndmask_b32_e64 v11, v172, 0, s[6:7]
	v_pk_fma_f32 v[4:5], v[84:85], v[114:115], v[4:5]
	v_pk_fma_f32 v[114:115], v[76:77], v[132:133], v[12:13]
	v_pk_fma_f32 v[116:117], v[82:83], v[118:119], v[14:15]
	v_pk_fma_f32 v[154:155], v[84:85], v[126:127], v[16:17]
	v_pk_fma_f32 v[124:125], v[80:81], v[102:103], v[20:21]
	v_pk_fma_f32 v[156:157], v[78:79], v[100:101], v[18:19]
	v_pk_fma_f32 v[158:159], v[74:75], v[104:105], v[22:23]
	v_cndmask_b32_e64 v6, v149, 0, s[6:7]
	v_cndmask_b32_e64 v8, v171, 0, s[6:7]
	v_cndmask_b32_e64 v10, v173, 0, s[6:7]
	v_lshlrev_b32_e32 v22, 16, v7
	v_and_b32_e32 v23, 0xffff0000, v7
	v_lshlrev_b32_e32 v18, 16, v9
	v_and_b32_e32 v19, 0xffff0000, v9
	v_lshlrev_b32_e32 v20, 16, v11
	v_and_b32_e32 v21, 0xffff0000, v11
	s_waitcnt vmcnt(5) lgkmcnt(6)
	v_cndmask_b32_e64 v9, v175, 0, s[16:17]
	v_cndmask_b32_e64 v7, v174, 0, s[16:17]
	s_waitcnt vmcnt(4) lgkmcnt(6)
	v_cndmask_b32_e64 v13, v177, 0, s[16:17]
	v_cndmask_b32_e64 v11, v176, 0, s[16:17]
	s_waitcnt vmcnt(3) lgkmcnt(6)
	v_cndmask_b32_e64 v17, v179, 0, s[16:17]
	v_cndmask_b32_e64 v15, v178, 0, s[16:17]
	s_cselect_b64 s[6:7], -1, 0
	s_add_i32 s16, s5, 3
	v_pk_fma_f32 v[128:129], v[76:77], v[106:107], v[24:25]
	v_pk_fma_f32 v[132:133], v[84:85], v[112:113], v[28:29]
	v_lshlrev_b32_e32 v28, 16, v8
	v_and_b32_e32 v29, 0xffff0000, v8
	v_lshlrev_b32_e32 v24, 16, v10
	v_and_b32_e32 v25, 0xffff0000, v10
	s_max_i32 s17, s16, 0
	v_pk_fma_f32 v[160:161], v[82:83], v[108:109], v[26:27]
	v_pk_fma_f32 v[146:147], v[78:79], v[120:121], v[30:31]
	v_lshlrev_b32_e32 v26, 16, v6
	v_and_b32_e32 v27, 0xffff0000, v6
	v_pk_fma_f32 v[42:43], v[78:79], v[18:19], v[42:43]
	v_pk_fma_f32 v[78:79], v[80:81], v[28:29], v[44:45]
	v_pk_fma_f32 v[44:45], v[76:77], v[24:25], v[48:49]
	v_mad_u64_u32 v[48:49], s[18:19], s17, v167, v[90:91]
	v_pk_fma_f32 v[32:33], v[80:81], v[122:123], v[32:33]
	v_pk_fma_f32 v[30:31], v[74:75], v[130:131], v[34:35]
	v_pk_fma_f32 v[34:35], v[76:77], v[134:135], v[36:37]
	v_pk_fma_f32 v[84:85], v[84:85], v[26:27], v[40:41]
	v_pk_fma_f32 v[40:41], v[74:75], v[20:21], v[46:47]
	v_lshlrev_b32_e32 v12, 16, v13
	v_and_b32_e32 v13, 0xffff0000, v13
	global_load_dwordx2 v[46:47], v[48:49], off
	s_waitcnt vmcnt(4) lgkmcnt(4)
	v_pk_fma_f32 v[76:77], v[60:61], v[102:103], v[110:111]
	v_pk_fma_f32 v[110:111], v[60:61], v[122:123], v[124:125]
	v_pk_fma_f32 v[124:125], v[52:53], v[26:27], v[132:133]
	global_load_dwordx2 v[132:133], v[48:49], off offset:512
	v_pk_fma_f32 v[36:37], v[52:53], v[126:127], v[4:5]
	v_pk_fma_f32 v[126:127], v[60:61], v[28:29], v[32:33]
	v_pk_fma_f32 v[60:61], v[60:61], v[12:13], v[78:79]
	global_load_dwordx2 v[78:79], v[48:49], off offset:1024
	s_waitcnt vmcnt(6) lgkmcnt(3)
	v_pk_fma_f32 v[80:81], v[54:55], v[104:105], v[152:153]
	v_pk_fma_f32 v[104:105], v[50:51], v[108:109], v[116:117]
	v_pk_fma_f32 v[116:117], v[56:57], v[134:135], v[128:129]
	v_pk_fma_f32 v[128:129], v[58:59], v[18:19], v[146:147]
	v_pk_fma_f32 v[146:147], v[54:55], v[20:21], v[30:31]
	ds_read_b128 v[30:33], v191 offset:9216
	v_lshlrev_b32_e32 v8, 16, v9
	v_and_b32_e32 v9, 0xffff0000, v9
	v_lshlrev_b32_e32 v14, 16, v15
	v_and_b32_e32 v15, 0xffff0000, v15
	v_add_co_u32_e32 v148, vcc, s14, v136
	s_waitcnt vmcnt(5) lgkmcnt(1)
	v_cndmask_b32_e64 v48, v145, 0, s[6:7]
	v_pk_fma_f32 v[82:83], v[82:83], v[22:23], v[38:39]
	v_lshlrev_b32_e32 v6, 16, v7
	v_and_b32_e32 v7, 0xffff0000, v7
	v_lshlrev_b32_e32 v10, 16, v11
	v_and_b32_e32 v11, 0xffff0000, v11
	v_lshlrev_b32_e32 v16, 16, v17
	v_and_b32_e32 v17, 0xffff0000, v17
	v_addc_co_u32_e32 v149, vcc, 0, v137, vcc
	v_pk_fma_f32 v[74:75], v[58:59], v[100:101], v[150:151]
	v_pk_fma_f32 v[100:101], v[56:57], v[106:107], v[114:115]
	v_pk_fma_f32 v[102:103], v[52:53], v[112:113], v[154:155]
	v_pk_fma_f32 v[114:115], v[54:55], v[130:131], v[158:159]
	v_pk_fma_f32 v[52:53], v[52:53], v[8:9], v[84:85]
	v_pk_fma_f32 v[54:55], v[54:55], v[14:15], v[40:41]
	v_cndmask_b32_e64 v40, v144, 0, s[6:7]
	v_lshlrev_b32_e32 v84, 16, v48
	v_and_b32_e32 v85, 0xffff0000, v48
	s_waitcnt vmcnt(4) lgkmcnt(1)
	v_cndmask_b32_e64 v48, v143, 0, s[6:7]
	v_cndmask_b32_e64 v49, v142, 0, s[6:7]
	s_cmp_lt_i32 s16, 0
	v_pk_fma_f32 v[38:39], v[50:51], v[118:119], v[2:3]
	ds_read_b128 v[2:5], v191 offset:20480
	v_pk_fma_f32 v[106:107], v[58:59], v[120:121], v[156:157]
	v_pk_fma_f32 v[118:119], v[50:51], v[22:23], v[160:161]
	v_pk_fma_f32 v[34:35], v[56:57], v[24:25], v[34:35]
	v_pk_fma_f32 v[82:83], v[50:51], v[6:7], v[82:83]
	v_pk_fma_f32 v[58:59], v[58:59], v[10:11], v[42:43]
	v_pk_fma_f32 v[44:45], v[56:57], v[16:17], v[44:45]
	v_lshlrev_b32_e32 v56, 16, v40
	v_and_b32_e32 v57, 0xffff0000, v40
	ds_read_b128 v[40:43], v191 offset:10240
	v_lshlrev_b32_e32 v142, 16, v49
	v_and_b32_e32 v143, 0xffff0000, v49
	v_lshlrev_b32_e32 v144, 16, v48
	v_and_b32_e32 v145, 0xffff0000, v48
	ds_read_b128 v[48:51], v191 offset:11264
	s_waitcnt vmcnt(3) lgkmcnt(4)
	v_cndmask_b32_e64 v87, v141, 0, s[6:7]
	v_cndmask_b32_e64 v139, v140, 0, s[6:7]
	s_cselect_b64 s[6:7], -1, 0
	s_add_i32 s18, s5, 4
	s_max_i32 s16, s18, 0
	v_pk_fma_f32 v[112:113], v[72:73], v[112:113], v[36:37]
	v_mad_u64_u32 v[36:37], s[16:17], s16, v167, v[90:91]
	v_pk_fma_f32 v[38:39], v[70:71], v[108:109], v[38:39]
	v_pk_fma_f32 v[108:109], v[68:69], v[28:29], v[110:111]
	v_pk_fma_f32 v[110:111], v[64:65], v[24:25], v[116:117]
	global_load_dwordx2 v[116:117], v[36:37], off
	v_pk_fma_f32 v[76:77], v[68:69], v[122:123], v[76:77]
	v_pk_fma_f32 v[122:123], v[66:67], v[10:11], v[128:129]
	global_load_dwordx2 v[128:129], v[36:37], off offset:512
	v_lshlrev_b32_e32 v140, 16, v87
	v_and_b32_e32 v141, 0xffff0000, v87
	v_pk_fma_f32 v[74:75], v[66:67], v[120:121], v[74:75]
	v_pk_fma_f32 v[104:105], v[70:71], v[22:23], v[104:105]
	v_pk_fma_f32 v[120:121], v[72:73], v[8:9], v[124:125]
	v_pk_fma_f32 v[118:119], v[70:71], v[6:7], v[118:119]
	v_pk_fma_f32 v[124:125], v[68:69], v[12:13], v[126:127]
	v_pk_fma_f32 v[70:71], v[70:71], v[56:57], v[82:83]
	v_pk_fma_f32 v[60:61], v[68:69], v[144:145], v[60:61]
	global_load_dwordx2 v[68:69], v[36:37], off offset:1024
	v_add_co_u32_e32 v82, vcc, s13, v136
	s_waitcnt vmcnt(4) lgkmcnt(4)
	v_cndmask_b32_e64 v87, v133, 0, s[6:7]
	s_cmp_lt_i32 s18, 0
	v_pk_fma_f32 v[80:81], v[62:63], v[130:131], v[80:81]
	v_pk_fma_f32 v[102:103], v[72:73], v[26:27], v[102:103]
	v_pk_fma_f32 v[130:131], v[64:65], v[16:17], v[34:35]
	v_pk_fma_f32 v[72:73], v[72:73], v[84:85], v[52:53]
	v_cndmask_b32_e64 v52, v47, 0, s[6:7]
	v_cndmask_b32_e64 v34, v46, 0, s[6:7]
	v_addc_co_u32_e32 v83, vcc, 0, v137, vcc
	v_cndmask_b32_e64 v132, v132, 0, s[6:7]
	v_lshlrev_b32_e32 v172, 16, v87
	v_and_b32_e32 v173, 0xffff0000, v87
	s_waitcnt vmcnt(3) lgkmcnt(4)
	v_cndmask_b32_e64 v87, v79, 0, s[6:7]
	v_cndmask_b32_e64 v79, v78, 0, s[6:7]
	s_cselect_b64 s[6:7], -1, 0
	s_add_i32 s18, s5, 5
	v_pk_fma_f32 v[100:101], v[64:65], v[134:135], v[100:101]
	v_add_co_u32_e32 v134, vcc, s12, v136
	s_max_i32 s16, s18, 0
	s_nop 0
	v_addc_co_u32_e32 v135, vcc, 0, v137, vcc
	s_waitcnt vmcnt(3) lgkmcnt(3)
	v_pk_fma_f32 v[38:39], v[30:31], v[22:23], v[38:39]
	v_mad_u64_u32 v[22:23], s[16:17], s16, v167, v[90:91]
	v_pk_fma_f32 v[106:107], v[66:67], v[18:19], v[106:107]
	v_pk_fma_f32 v[126:127], v[62:63], v[14:15], v[146:147]
	v_pk_fma_f32 v[58:59], v[66:67], v[142:143], v[58:59]
	v_pk_fma_f32 v[64:65], v[64:65], v[140:141], v[44:45]
	v_lshlrev_b32_e32 v66, 16, v34
	v_and_b32_e32 v67, 0xffff0000, v34
	ds_read_b128 v[44:47], v191 offset:13312
	v_lshlrev_b32_e32 v170, 16, v132
	v_and_b32_e32 v171, 0xffff0000, v132
	global_load_dwordx2 v[132:133], v[22:23], off
	global_load_dwordx2 v[146:147], v[22:23], off offset:512
	global_load_dwordx2 v[176:177], v[22:23], off offset:1024
	ds_read_b128 v[34:37], v191 offset:12288
	s_cmp_lt_i32 s18, 0
	v_lshlrev_b32_e32 v138, 16, v139
	v_and_b32_e32 v139, 0xffff0000, v139
	s_cselect_b64 s[16:17], -1, 0
	s_add_i32 s20, s5, 6
	v_pk_fma_f32 v[114:115], v[62:63], v[20:21], v[114:115]
	v_pk_fma_f32 v[62:63], v[62:63], v[138:139], v[54:55]
	v_lshlrev_b32_e32 v136, 16, v52
	s_waitcnt vmcnt(6) lgkmcnt(3)
	v_pk_fma_f32 v[74:75], v[40:41], v[18:19], v[74:75]
	v_pk_fma_f32 v[106:107], v[40:41], v[10:11], v[106:107]
	v_pk_fma_f32 v[122:123], v[40:41], v[142:143], v[122:123]
	v_pk_fma_f32 v[40:41], v[40:41], v[170:171], v[58:59]
	v_and_b32_e32 v137, 0xffff0000, v52
	ds_read_b128 v[52:55], v191 offset:14336
	v_lshlrev_b32_e32 v78, 16, v79
	v_and_b32_e32 v79, 0xffff0000, v79
	s_max_i32 s18, s20, 0
	s_waitcnt vmcnt(6) lgkmcnt(3)
	v_pk_fma_f32 v[80:81], v[48:49], v[20:21], v[80:81]
	v_pk_fma_f32 v[114:115], v[48:49], v[14:15], v[114:115]
	v_pk_fma_f32 v[126:127], v[48:49], v[138:139], v[126:127]
	v_pk_fma_f32 v[48:49], v[48:49], v[78:79], v[62:63]
	v_pk_fma_f32 v[76:77], v[42:43], v[28:29], v[76:77]
	v_pk_fma_f32 v[108:109], v[42:43], v[12:13], v[108:109]
	v_pk_fma_f32 v[124:125], v[42:43], v[144:145], v[124:125]
	ds_read_b128 v[18:21], v191 offset:15360
	s_waitcnt vmcnt(5) lgkmcnt(4)
	v_cndmask_b32_e64 v58, v117, 0, s[6:7]
	v_cndmask_b32_e64 v59, v116, 0, s[6:7]
	v_lshlrev_b32_e32 v152, 16, v58
	v_and_b32_e32 v153, 0xffff0000, v58
	s_waitcnt vmcnt(4) lgkmcnt(4)
	v_cndmask_b32_e64 v58, v128, 0, s[6:7]
	v_lshlrev_b32_e32 v150, 16, v59
	v_and_b32_e32 v151, 0xffff0000, v59
	v_cndmask_b32_e64 v62, v129, 0, s[6:7]
	v_lshlrev_b32_e32 v154, 16, v58
	v_and_b32_e32 v155, 0xffff0000, v58
	v_mad_u64_u32 v[58:59], s[18:19], s18, v167, v[90:91]
	v_pk_fma_f32 v[42:43], v[42:43], v[172:173], v[60:61]
	v_lshlrev_b32_e32 v156, 16, v62
	global_load_dwordx2 v[60:61], v[58:59], off
	v_and_b32_e32 v157, 0xffff0000, v62
	s_waitcnt vmcnt(4) lgkmcnt(4)
	v_cndmask_b32_e64 v62, v68, 0, s[6:7]
	v_pk_fma_f32 v[112:113], v[32:33], v[26:27], v[112:113]
	ds_read_b128 v[26:29], v191 offset:17408
	v_lshlrev_b32_e32 v158, 16, v62
	v_and_b32_e32 v159, 0xffff0000, v62
	global_load_dwordx2 v[62:63], v[58:59], off offset:512
	v_lshlrev_b32_e32 v174, 16, v87
	v_and_b32_e32 v175, 0xffff0000, v87
	v_pk_fma_f32 v[100:101], v[50:51], v[24:25], v[100:101]
	ds_read_b128 v[22:25], v191 offset:16384
	v_pk_fma_f32 v[110:111], v[50:51], v[16:17], v[110:111]
	global_load_dwordx2 v[58:59], v[58:59], off offset:1024
	v_pk_fma_f32 v[130:131], v[50:51], v[140:141], v[130:131]
	v_pk_fma_f32 v[50:51], v[50:51], v[174:175], v[64:65]
	v_cndmask_b32_e64 v64, v69, 0, s[6:7]
	v_pk_fma_f32 v[102:103], v[32:33], v[8:9], v[102:103]
	v_pk_fma_f32 v[104:105], v[30:31], v[6:7], v[104:105]
	v_pk_fma_f32 v[118:119], v[30:31], v[56:57], v[118:119]
	v_pk_fma_f32 v[30:31], v[30:31], v[66:67], v[70:71]
	v_lshlrev_b32_e32 v160, 16, v64
	v_and_b32_e32 v161, 0xffff0000, v64
	v_pk_fma_f32 v[120:121], v[32:33], v[84:85], v[120:121]
	v_pk_fma_f32 v[32:33], v[32:33], v[136:137], v[72:73]
	s_cmp_lt_i32 s20, 0
	s_cselect_b64 s[6:7], -1, 0
	s_cmp_eq_u32 s0, 0x12000
	s_waitcnt vmcnt(6) lgkmcnt(5)
	v_pk_fma_f32 v[68:69], v[44:45], v[10:11], v[74:75]
	v_pk_fma_f32 v[70:71], v[46:47], v[12:13], v[76:77]
	ds_read_b128 v[10:13], v191 offset:19456
	v_pk_fma_f32 v[76:77], v[46:47], v[144:145], v[108:109]
	v_pk_fma_f32 v[108:109], v[46:47], v[172:173], v[124:125]
	s_waitcnt vmcnt(3) lgkmcnt(5)
	v_pk_fma_f32 v[38:39], v[34:35], v[6:7], v[38:39]
	v_pk_fma_f32 v[64:65], v[36:37], v[8:9], v[112:113]
	ds_read_b128 v[6:9], v191 offset:18432
	v_pk_fma_f32 v[72:73], v[36:37], v[84:85], v[102:103]
	v_pk_fma_f32 v[102:103], v[36:37], v[136:137], v[120:121]
	v_pk_fma_f32 v[32:33], v[36:37], v[152:153], v[32:33]
	v_pk_fma_f32 v[36:37], v[44:45], v[154:155], v[40:41]
	v_pk_fma_f32 v[74:75], v[34:35], v[56:57], v[104:105]
	v_pk_fma_f32 v[104:105], v[34:35], v[66:67], v[118:119]
	v_pk_fma_f32 v[30:31], v[34:35], v[150:151], v[30:31]
	v_pk_fma_f32 v[34:35], v[46:47], v[156:157], v[42:43]
	s_waitcnt vmcnt(3) lgkmcnt(5)
	v_pk_fma_f32 v[14:15], v[52:53], v[14:15], v[80:81]
	v_pk_fma_f32 v[80:81], v[44:45], v[142:143], v[106:107]
	v_pk_fma_f32 v[106:107], v[44:45], v[170:171], v[122:123]
	v_cndmask_b32_e64 v45, v132, 0, s[16:17]
	v_pk_fma_f32 v[82:83], v[54:55], v[140:141], v[110:111]
	v_cndmask_b32_e64 v44, v133, 0, s[16:17]
	v_lshlrev_b32_e32 v110, 16, v45
	v_and_b32_e32 v111, 0xffff0000, v45
	v_pk_fma_f32 v[16:17], v[54:55], v[16:17], v[100:101]
	v_pk_fma_f32 v[100:101], v[52:53], v[138:139], v[114:115]
	v_pk_fma_f32 v[112:113], v[52:53], v[78:79], v[126:127]
	v_pk_fma_f32 v[118:119], v[54:55], v[174:175], v[130:131]
	v_pk_fma_f32 v[40:41], v[54:55], v[160:161], v[50:51]
	v_pk_fma_f32 v[42:43], v[52:53], v[158:159], v[48:49]
	v_lshlrev_b32_e32 v114, 16, v44
	v_and_b32_e32 v115, 0xffff0000, v44
	v_cndmask_b32_e64 v44, v147, 0, s[16:17]
	v_cndmask_b32_e64 v45, v146, 0, s[16:17]
	s_waitcnt vmcnt(3) lgkmcnt(4)
	v_pk_fma_f32 v[38:39], v[18:19], v[56:57], v[38:39]
	v_pk_fma_f32 v[50:51], v[20:21], v[136:137], v[72:73]
	v_pk_fma_f32 v[52:53], v[18:19], v[66:67], v[74:75]
	v_pk_fma_f32 v[72:73], v[18:19], v[150:151], v[104:105]
	v_pk_fma_f32 v[18:19], v[18:19], v[110:111], v[30:31]
	v_lshlrev_b32_e32 v116, 16, v45
	v_and_b32_e32 v117, 0xffff0000, v45
	v_lshlrev_b32_e32 v124, 16, v44
	s_waitcnt vmcnt(2) lgkmcnt(4)
	v_cndmask_b32_e64 v30, v61, 0, s[6:7]
	v_cndmask_b32_e64 v31, v60, 0, s[6:7]
	v_and_b32_e32 v125, 0xffff0000, v44
	v_cndmask_b32_e64 v44, v177, 0, s[16:17]
	v_cndmask_b32_e64 v45, v176, 0, s[16:17]
	s_waitcnt vmcnt(2) lgkmcnt(3)
	v_pk_fma_f32 v[122:123], v[28:29], v[160:161], v[118:119]
	v_lshlrev_b32_e32 v118, 16, v31
	v_and_b32_e32 v119, 0xffff0000, v31
	v_lshlrev_b32_e32 v126, 16, v30
	v_and_b32_e32 v127, 0xffff0000, v30
	s_waitcnt vmcnt(1) lgkmcnt(3)
	v_cndmask_b32_e64 v30, v63, 0, s[6:7]
	v_cndmask_b32_e64 v31, v62, 0, s[6:7]
	v_lshlrev_b32_e32 v128, 16, v45
	v_and_b32_e32 v129, 0xffff0000, v45
	v_lshlrev_b32_e32 v132, 16, v44
	v_and_b32_e32 v133, 0xffff0000, v44
	s_waitcnt vmcnt(1) lgkmcnt(2)
	v_pk_fma_f32 v[46:47], v[24:25], v[144:145], v[70:71]
	v_pk_fma_f32 v[48:49], v[22:23], v[142:143], v[68:69]
	v_pk_fma_f32 v[68:69], v[26:27], v[78:79], v[100:101]
	v_pk_fma_f32 v[70:71], v[20:21], v[152:153], v[102:103]
	v_lshlrev_b32_e32 v100, 16, v31
	v_and_b32_e32 v101, 0xffff0000, v31
	v_lshlrev_b32_e32 v102, 16, v30
	v_and_b32_e32 v103, 0xffff0000, v30
	s_waitcnt vmcnt(0) lgkmcnt(2)
	v_cndmask_b32_e64 v30, v59, 0, s[6:7]
	v_cndmask_b32_e64 v31, v58, 0, s[6:7]
	v_pk_fma_f32 v[44:45], v[20:21], v[84:85], v[64:65]
	v_pk_fma_f32 v[16:17], v[28:29], v[140:141], v[16:17]
	v_pk_fma_f32 v[14:15], v[26:27], v[138:139], v[14:15]
	v_pk_fma_f32 v[54:55], v[24:25], v[172:173], v[76:77]
	v_pk_fma_f32 v[56:57], v[22:23], v[170:171], v[80:81]
	v_pk_fma_f32 v[64:65], v[28:29], v[174:175], v[82:83]
	v_pk_fma_f32 v[108:109], v[24:25], v[156:157], v[108:109]
	v_pk_fma_f32 v[120:121], v[22:23], v[154:155], v[106:107]
	v_pk_fma_f32 v[112:113], v[26:27], v[158:159], v[112:113]
	v_pk_fma_f32 v[20:21], v[20:21], v[114:115], v[32:33]
	v_pk_fma_f32 v[24:25], v[24:25], v[124:125], v[34:35]
	v_pk_fma_f32 v[22:23], v[22:23], v[116:117], v[36:37]
	v_pk_fma_f32 v[28:29], v[28:29], v[132:133], v[40:41]
	v_pk_fma_f32 v[26:27], v[26:27], v[128:129], v[42:43]
	v_lshlrev_b32_e32 v104, 16, v31
	v_and_b32_e32 v105, 0xffff0000, v31
	v_lshlrev_b32_e32 v106, 16, v30
	v_and_b32_e32 v107, 0xffff0000, v30
	s_waitcnt vmcnt(0) lgkmcnt(0)
	v_pk_fma_f32 v[144:145], v[6:7], v[66:67], v[38:39]
	v_pk_fma_f32 v[146:147], v[8:9], v[136:137], v[44:45]
	v_pk_fma_f32 v[142:143], v[10:11], v[170:171], v[48:49]
	v_pk_fma_f32 v[140:141], v[12:13], v[172:173], v[46:47]
	v_pk_fma_f32 v[138:139], v[2:3], v[78:79], v[14:15]
	v_pk_fma_f32 v[136:137], v[4:5], v[174:175], v[16:17]
	v_pk_fma_f32 v[82:83], v[8:9], v[152:153], v[50:51]
	v_pk_fma_f32 v[84:85], v[6:7], v[150:151], v[52:53]
	v_pk_fma_f32 v[78:79], v[12:13], v[156:157], v[54:55]
	v_pk_fma_f32 v[80:81], v[10:11], v[154:155], v[56:57]
	v_pk_fma_f32 v[74:75], v[4:5], v[160:161], v[64:65]
	v_pk_fma_f32 v[76:77], v[2:3], v[158:159], v[68:69]
	v_pk_fma_f32 v[70:71], v[8:9], v[114:115], v[70:71]
	v_pk_fma_f32 v[72:73], v[6:7], v[110:111], v[72:73]
	v_pk_fma_f32 v[68:69], v[10:11], v[116:117], v[120:121]
	v_pk_fma_f32 v[66:67], v[12:13], v[124:125], v[108:109]
	v_pk_fma_f32 v[64:65], v[2:3], v[128:129], v[112:113]
	v_pk_fma_f32 v[62:63], v[4:5], v[132:133], v[122:123]
	v_pk_fma_f32 v[58:59], v[8:9], v[126:127], v[20:21]
	v_pk_fma_f32 v[60:61], v[6:7], v[118:119], v[18:19]
	v_pk_fma_f32 v[54:55], v[12:13], v[102:103], v[24:25]
	v_pk_fma_f32 v[56:57], v[10:11], v[100:101], v[22:23]
	v_pk_fma_f32 v[50:51], v[4:5], v[106:107], v[28:29]
	v_pk_fma_f32 v[52:53], v[2:3], v[104:105], v[26:27]
	s_mov_b64 s[6:7], -1
	v_readfirstlane_b32 s16, v0
	s_cbranch_scc1 .LBB0_277
	s_add_i32 s16, s5, 7
	s_max_i32 s6, s16, 0
	v_mad_u64_u32 v[2:3], s[6:7], s6, v167, v[90:91]
	ds_read_b128 v[38:41], v191 offset:21504
	ds_read_b128 v[42:45], v191 offset:22528
	ds_read_b128 v[46:49], v191 offset:23552
	global_load_dwordx2 v[108:109], v[2:3], off
	global_load_dwordx2 v[112:113], v[2:3], off offset:512
	global_load_dwordx2 v[120:121], v[2:3], off offset:1024
	s_cmp_lt_i32 s16, 0
	s_cselect_b64 s[6:7], -1, 0
	s_add_u32 s0, s0, 0x6000
	s_addc_u32 s1, s1, 0
	s_add_i32 s16, s5, 8
	s_waitcnt vmcnt(3) lgkmcnt(2)
	v_pk_fma_f32 v[4:5], v[40:41], v[152:153], v[146:147]
	s_waitcnt vmcnt(2) lgkmcnt(0)
	v_cndmask_b32_e64 v87, v109, 0, s[6:7]
	v_cndmask_b32_e64 v109, v108, 0, s[6:7]
	s_waitcnt vmcnt(1) lgkmcnt(0)
	v_cndmask_b32_e64 v123, v113, 0, s[6:7]
	v_cndmask_b32_e64 v122, v112, 0, s[6:7]
	s_waitcnt vmcnt(0) lgkmcnt(0)
	v_cndmask_b32_e64 v135, v121, 0, s[6:7]
	v_cndmask_b32_e64 v131, v120, 0, s[6:7]
	v_lshlrev_b32_e32 v108, 16, v109
	v_and_b32_e32 v109, 0xffff0000, v109
	v_lshlrev_b32_e32 v112, 16, v87
	v_and_b32_e32 v113, 0xffff0000, v87
	v_lshlrev_b32_e32 v120, 16, v122
	v_and_b32_e32 v121, 0xffff0000, v122
	v_lshlrev_b32_e32 v122, 16, v123
	v_and_b32_e32 v123, 0xffff0000, v123
	v_lshlrev_b32_e32 v130, 16, v131
	v_and_b32_e32 v131, 0xffff0000, v131
	v_lshlrev_b32_e32 v134, 16, v135
	v_and_b32_e32 v135, 0xffff0000, v135
	v_pk_fma_f32 v[2:3], v[38:39], v[150:151], v[144:145]
	v_pk_fma_f32 v[8:9], v[44:45], v[156:157], v[140:141]
	v_pk_fma_f32 v[6:7], v[42:43], v[154:155], v[142:143]
	v_pk_fma_f32 v[12:13], v[48:49], v[160:161], v[136:137]
	v_pk_fma_f32 v[10:11], v[46:47], v[158:159], v[138:139]
	v_pk_fma_f32 v[16:17], v[40:41], v[114:115], v[82:83]
	v_pk_fma_f32 v[14:15], v[38:39], v[110:111], v[84:85]
	v_pk_fma_f32 v[20:21], v[44:45], v[124:125], v[78:79]
	v_pk_fma_f32 v[18:19], v[42:43], v[116:117], v[80:81]
	v_pk_fma_f32 v[24:25], v[48:49], v[132:133], v[74:75]
	v_pk_fma_f32 v[22:23], v[46:47], v[128:129], v[76:77]
	v_pk_fma_f32 v[28:29], v[40:41], v[126:127], v[70:71]
	v_pk_fma_f32 v[26:27], v[38:39], v[118:119], v[72:73]
	v_pk_fma_f32 v[32:33], v[44:45], v[102:103], v[66:67]
	v_pk_fma_f32 v[30:31], v[42:43], v[100:101], v[68:69]
	v_pk_fma_f32 v[36:37], v[48:49], v[106:107], v[62:63]
	v_pk_fma_f32 v[34:35], v[46:47], v[104:105], v[64:65]
	v_pk_fma_f32 v[40:41], v[40:41], v[112:113], v[58:59]
	v_pk_fma_f32 v[38:39], v[38:39], v[108:109], v[60:61]
	v_pk_fma_f32 v[44:45], v[44:45], v[122:123], v[54:55]
	v_pk_fma_f32 v[42:43], v[42:43], v[120:121], v[56:57]
	v_pk_fma_f32 v[48:49], v[48:49], v[134:135], v[50:51]
	v_pk_fma_f32 v[46:47], v[46:47], v[130:131], v[52:53]
	s_mov_b64 s[6:7], 0
	s_branch .LBB0_277
